# EpiUpConv: vmcnt(0) behind two stores relaxed to vmcnt(2) (only conv-weight loads are needed)
# speedup vs baseline: 1.0048x; 1.0048x over previous
.LBB0_777:
	s_or_b64 exec, exec, s[44:45]
	v_lshlrev_b64 v[150:151], 1, v[192:193]
	v_lshl_add_u64 v[152:153], v[220:221], 0, v[150:151]
	s_waitcnt lgkmcnt(0)
	v_pk_mul_f32 v[108:109], v[108:109], v[214:215] op_sel_hi:[1,0]
	global_store_dwordx4 v[152:153], v[144:147], off sc1
	ds_bpermute_b32 v144, v173, v108
	ds_bpermute_b32 v145, v175, v108
	v_cmp_eq_u32_e64 s[46:47], 0, v176
	s_waitcnt vmcnt(2)
	v_fma_f32 v108, v140, v108, v128
	ds_bpermute_b32 v146, v173, v109
	s_waitcnt lgkmcnt(2)
	v_cndmask_b32_e64 v158, v144, v225, s[46:47]
	s_waitcnt lgkmcnt(1)
	v_cndmask_b32_e32 v159, v145, v224, vcc
	v_fmac_f32_e32 v108, v136, v158
	ds_bpermute_b32 v147, v175, v109
	v_fmac_f32_e32 v108, v132, v159
	v_mul_f32_e32 v158, 0xbfb8aa3b, v108
	v_exp_f32_e32 v158, v158
	v_pk_mul_f32 v[110:111], v[110:111], v[214:215] op_sel_hi:[1,0]
	ds_bpermute_b32 v153, v173, v110
	s_waitcnt lgkmcnt(2)
	v_cndmask_b32_e64 v159, v146, v222, s[46:47]
	v_fma_f32 v109, v141, v109, v129
	ds_bpermute_b32 v152, v173, v111
	ds_bpermute_b32 v154, v175, v110
	s_waitcnt lgkmcnt(3)
	v_cndmask_b32_e32 v179, v147, v215, vcc
	v_fmac_f32_e32 v109, v137, v159
	ds_bpermute_b32 v155, v175, v111
	v_add_f32_e32 v158, 1.0, v158
	v_fmac_f32_e32 v109, v133, v179
	v_rcp_f32_e32 v158, v158
	v_mul_f32_e32 v159, 0xbfb8aa3b, v109
	v_exp_f32_e32 v159, v159
	s_waitcnt lgkmcnt(3)
	v_cndmask_b32_e64 v157, v153, v226, s[46:47]
	v_fma_f32 v110, v142, v110, v130
	s_waitcnt lgkmcnt(2)
	v_cndmask_b32_e64 v156, v152, v227, s[46:47]
	s_waitcnt lgkmcnt(1)
	v_cndmask_b32_e32 v179, v154, v213, vcc
	v_fmac_f32_e32 v110, v138, v157
	v_fma_f32 v111, v143, v111, v131
	v_pk_mul_f32 v[104:105], v[104:105], v[214:215] op_sel_hi:[1,0]
	s_waitcnt lgkmcnt(0)
	v_cndmask_b32_e32 v178, v155, v223, vcc
	v_mul_f32_e32 v108, v108, v158
	v_fmac_f32_e32 v110, v134, v179
	v_fmac_f32_e32 v111, v139, v156
	v_mul_f32_e32 v104, v104, v108
	v_add_f32_e32 v108, 1.0, v159
	v_mul_f32_e32 v157, 0xbfb8aa3b, v110
	v_fmac_f32_e32 v111, v135, v178
	v_rcp_f32_e32 v108, v108
	v_exp_f32_e32 v157, v157
	v_mul_f32_e32 v156, 0xbfb8aa3b, v111
	v_exp_f32_e32 v156, v156
	v_pk_mul_f32 v[102:103], v[102:103], v[214:215] op_sel_hi:[1,0]
	v_mul_f32_e32 v108, v109, v108
	v_add_f32_e32 v109, 1.0, v157
	ds_bpermute_b32 v157, v173, v103
	v_rcp_f32_e32 v109, v109
	v_add_f32_e32 v156, 1.0, v156
	ds_bpermute_b32 v158, v175, v103
	v_rcp_f32_e32 v156, v156
	v_pk_mul_f32 v[106:107], v[106:107], v[214:215] op_sel_hi:[1,0]
	v_mul_f32_e32 v105, v105, v108
	v_mul_f32_e32 v108, v110, v109
	s_waitcnt lgkmcnt(1)
	v_cndmask_b32_e64 v180, v157, v211, s[46:47]
	v_fma_f32 v103, v127, v103, v115
	v_mul_f32_e32 v106, v106, v108
	v_mul_f32_e32 v108, v111, v156
	ds_bpermute_b32 v156, v173, v102
	s_waitcnt lgkmcnt(1)
	v_cndmask_b32_e32 v181, v158, v209, vcc
	v_fmac_f32_e32 v103, v123, v180
	ds_bpermute_b32 v159, v175, v102
	v_fmac_f32_e32 v103, v119, v181
	v_mul_f32_e32 v180, 0xbfb8aa3b, v103
	v_exp_f32_e32 v180, v180
	v_pk_mul_f32 v[100:101], v[100:101], v[214:215] op_sel_hi:[1,0]
	ds_bpermute_b32 v110, v173, v101
	s_waitcnt lgkmcnt(2)
	v_cndmask_b32_e64 v181, v156, v197, s[46:47]
	v_fma_f32 v102, v126, v102, v114
	v_mul_f32_e32 v107, v107, v108
	ds_bpermute_b32 v108, v173, v100
	ds_bpermute_b32 v111, v175, v101
	s_waitcnt lgkmcnt(3)
	v_cndmask_b32_e32 v182, v159, v201, vcc
	v_fmac_f32_e32 v102, v122, v181
	ds_bpermute_b32 v109, v175, v100
	v_add_f32_e32 v180, 1.0, v180
	v_fmac_f32_e32 v102, v118, v182
	v_rcp_f32_e32 v180, v180
	v_mul_f32_e32 v181, 0xbfb8aa3b, v102
	v_exp_f32_e32 v181, v181
	s_waitcnt lgkmcnt(3)
	v_cndmask_b32_e64 v179, v110, v205, s[46:47]
	v_fma_f32 v101, v125, v101, v113
	s_waitcnt lgkmcnt(2)
	v_cndmask_b32_e64 v178, v108, v203, s[46:47]
	s_waitcnt lgkmcnt(1)
	v_cndmask_b32_e32 v182, v111, v191, vcc
	v_fmac_f32_e32 v101, v121, v179
	v_fma_f32 v100, v124, v100, v112
	v_pk_mul_f32 v[98:99], v[98:99], v[214:215] op_sel_hi:[1,0]
	s_waitcnt lgkmcnt(0)
	v_cndmask_b32_e32 v183, v109, v195, vcc
	v_mul_f32_e32 v103, v103, v180
	v_fmac_f32_e32 v101, v117, v182
	v_fmac_f32_e32 v100, v120, v178
	v_mul_f32_e32 v103, v99, v103
	v_add_f32_e32 v99, 1.0, v181
	v_mul_f32_e32 v179, 0xbfb8aa3b, v101
	v_fmac_f32_e32 v100, v116, v183
	v_rcp_f32_e32 v99, v99
	v_exp_f32_e32 v179, v179
	v_mul_f32_e32 v178, 0xbfb8aa3b, v100
	v_exp_f32_e32 v178, v178
	v_mul_f32_e32 v99, v102, v99
	v_add_f32_e32 v102, 1.0, v179
	v_rcp_f32_e32 v102, v102
	v_add_f32_e32 v178, 1.0, v178
	v_rcp_f32_e32 v178, v178
	v_pk_mul_f32 v[96:97], v[96:97], v[214:215] op_sel_hi:[1,0]
	v_mul_f32_e32 v179, v98, v99
	v_mul_f32_e32 v98, v101, v102
	v_mul_f32_e32 v97, v97, v98
	v_mul_f32_e32 v98, v100, v178
	v_mul_f32_e32 v96, v96, v98
	v_cvt_pk_bf16_f32 v98, v104, v105
	v_cvt_pk_bf16_f32 v99, v106, v107
	v_cvt_pk_bf16_f32 v100, v96, v97
	v_mov_b64_e32 v[96:97], s[52:53]
	v_cvt_pk_bf16_f32 v101, v179, v103
	v_mad_i64_i32 v[102:103], s[6:7], v204, s25, v[96:97]
	v_lshl_add_u64 v[102:103], v[102:103], 0, v[150:151]
	v_pk_mul_f32 v[92:93], v[92:93], v[212:213] op_sel_hi:[1,0]
	global_store_dwordx4 v[102:103], v[98:101], off sc1
	ds_bpermute_b32 v98, v173, v92
	ds_bpermute_b32 v99, v175, v92
	v_fma_f32 v92, v140, v92, v128
	ds_bpermute_b32 v100, v173, v93
	ds_bpermute_b32 v103, v175, v93
	s_waitcnt lgkmcnt(3)
	v_cndmask_b32_e64 v144, v98, v144, s[46:47]
	s_waitcnt lgkmcnt(2)
	v_cndmask_b32_e32 v145, v99, v145, vcc
	v_fmac_f32_e32 v92, v136, v144
	v_fmac_f32_e32 v92, v132, v145
	v_mul_f32_e32 v144, 0xbfb8aa3b, v92
	v_exp_f32_e32 v144, v144
	v_pk_mul_f32 v[94:95], v[94:95], v[212:213] op_sel_hi:[1,0]
	ds_bpermute_b32 v102, v173, v94
	s_waitcnt lgkmcnt(2)
	v_cndmask_b32_e64 v145, v100, v146, s[46:47]
	v_fma_f32 v93, v141, v93, v129
	ds_bpermute_b32 v101, v173, v95
	ds_bpermute_b32 v104, v175, v94
	s_waitcnt lgkmcnt(3)
	v_cndmask_b32_e32 v147, v103, v147, vcc
	v_fmac_f32_e32 v93, v137, v145
	ds_bpermute_b32 v105, v175, v95
	v_add_f32_e32 v144, 1.0, v144
	v_fmac_f32_e32 v93, v133, v147
	v_rcp_f32_e32 v144, v144
	v_mul_f32_e32 v145, 0xbfb8aa3b, v93
	v_exp_f32_e32 v145, v145
	s_waitcnt lgkmcnt(3)
	v_cndmask_b32_e64 v107, v102, v153, s[46:47]
	v_fma_f32 v94, v142, v94, v130
	s_waitcnt lgkmcnt(2)
	v_cndmask_b32_e64 v106, v101, v152, s[46:47]
	s_waitcnt lgkmcnt(1)
	v_cndmask_b32_e32 v147, v104, v154, vcc
	v_fmac_f32_e32 v94, v138, v107
	v_fma_f32 v95, v143, v95, v131
	v_pk_mul_f32 v[88:89], v[88:89], v[212:213] op_sel_hi:[1,0]
	s_waitcnt lgkmcnt(0)
	v_cndmask_b32_e32 v146, v105, v155, vcc
	v_mul_f32_e32 v92, v92, v144
	v_fmac_f32_e32 v94, v134, v147
	v_fmac_f32_e32 v95, v139, v106
	v_mul_f32_e32 v88, v88, v92
	v_add_f32_e32 v92, 1.0, v145
	v_mul_f32_e32 v107, 0xbfb8aa3b, v94
	v_fmac_f32_e32 v95, v135, v146
	v_rcp_f32_e32 v92, v92
	v_exp_f32_e32 v107, v107
	v_mul_f32_e32 v106, 0xbfb8aa3b, v95
	v_exp_f32_e32 v106, v106
	v_pk_mul_f32 v[86:87], v[86:87], v[212:213] op_sel_hi:[1,0]
	v_mul_f32_e32 v92, v93, v92
	v_add_f32_e32 v93, 1.0, v107
	ds_bpermute_b32 v107, v173, v87
	v_rcp_f32_e32 v93, v93
	v_add_f32_e32 v106, 1.0, v106
	ds_bpermute_b32 v144, v175, v87
	v_rcp_f32_e32 v106, v106
	v_pk_mul_f32 v[90:91], v[90:91], v[212:213] op_sel_hi:[1,0]
	v_mul_f32_e32 v89, v89, v92
	v_mul_f32_e32 v92, v94, v93
	s_waitcnt lgkmcnt(1)
	v_cndmask_b32_e64 v146, v107, v157, s[46:47]
	v_fma_f32 v87, v127, v87, v115
	v_mul_f32_e32 v90, v90, v92
	v_mul_f32_e32 v92, v95, v106
	ds_bpermute_b32 v106, v173, v86
	s_waitcnt lgkmcnt(1)
	v_cndmask_b32_e32 v147, v144, v158, vcc
	v_fmac_f32_e32 v87, v123, v146
	ds_bpermute_b32 v145, v175, v86
	v_fmac_f32_e32 v87, v119, v147
	v_mul_f32_e32 v146, 0xbfb8aa3b, v87
	v_exp_f32_e32 v146, v146
	v_pk_mul_f32 v[84:85], v[84:85], v[212:213] op_sel_hi:[1,0]
	ds_bpermute_b32 v94, v173, v85
	s_waitcnt lgkmcnt(2)
	v_cndmask_b32_e64 v147, v106, v156, s[46:47]
	v_fma_f32 v86, v126, v86, v114
	v_mul_f32_e32 v91, v91, v92
	ds_bpermute_b32 v92, v173, v84
	ds_bpermute_b32 v95, v175, v85
	s_waitcnt lgkmcnt(3)
	v_cndmask_b32_e32 v152, v145, v159, vcc
	v_fmac_f32_e32 v86, v122, v147
	ds_bpermute_b32 v93, v175, v84
	v_add_f32_e32 v146, 1.0, v146
	v_fmac_f32_e32 v86, v118, v152
	v_rcp_f32_e32 v146, v146
	v_mul_f32_e32 v147, 0xbfb8aa3b, v86
	v_exp_f32_e32 v147, v147
	s_waitcnt lgkmcnt(3)
	v_cndmask_b32_e64 v110, v94, v110, s[46:47]
	v_fma_f32 v85, v125, v85, v113
	s_waitcnt lgkmcnt(2)
	v_cndmask_b32_e64 v108, v92, v108, s[46:47]
	s_waitcnt lgkmcnt(1)
	v_cndmask_b32_e32 v111, v95, v111, vcc
	v_fmac_f32_e32 v85, v121, v110
	v_fma_f32 v84, v124, v84, v112
	v_pk_mul_f32 v[82:83], v[82:83], v[212:213] op_sel_hi:[1,0]
	s_waitcnt lgkmcnt(0)
	v_cndmask_b32_e32 v109, v93, v109, vcc
	v_mul_f32_e32 v87, v87, v146
	v_fmac_f32_e32 v85, v117, v111
	v_fmac_f32_e32 v84, v120, v108
	v_mul_f32_e32 v83, v83, v87
	v_add_f32_e32 v87, 1.0, v147
	v_mul_f32_e32 v110, 0xbfb8aa3b, v85
	v_fmac_f32_e32 v84, v116, v109
	v_rcp_f32_e32 v87, v87
	v_exp_f32_e32 v110, v110
	v_mul_f32_e32 v108, 0xbfb8aa3b, v84
	v_exp_f32_e32 v108, v108
	v_mul_f32_e32 v86, v86, v87
	v_add_f32_e32 v87, 1.0, v110
	v_rcp_f32_e32 v87, v87
	v_add_f32_e32 v108, 1.0, v108
	v_rcp_f32_e32 v108, v108
	v_pk_mul_f32 v[80:81], v[80:81], v[212:213] op_sel_hi:[1,0]
	v_mul_f32_e32 v86, v82, v86
	v_mul_f32_e32 v82, v85, v87
	v_mul_f32_e32 v82, v81, v82
	v_mul_f32_e32 v81, v84, v108
	v_mul_f32_e32 v84, v80, v81
	v_cvt_pk_bf16_f32 v80, v88, v89
	v_cvt_pk_bf16_f32 v81, v90, v91
	v_cvt_pk_bf16_f32 v82, v84, v82
	v_mad_i64_i32 v[84:85], s[6:7], v200, s25, v[96:97]
	v_lshl_add_u64 v[84:85], v[84:85], 0, v[150:151]
	v_pk_mul_f32 v[76:77], v[76:77], v[210:211] op_sel_hi:[1,0]
	v_cvt_pk_bf16_f32 v83, v86, v83
	global_store_dwordx4 v[84:85], v[80:83], off sc1
	ds_bpermute_b32 v80, v173, v76
	ds_bpermute_b32 v81, v175, v76
	v_pk_mul_f32 v[78:79], v[78:79], v[210:211] op_sel_hi:[1,0]
	v_fma_f32 v88, v140, v76, v128
	ds_bpermute_b32 v82, v173, v77
	s_waitcnt lgkmcnt(2)
	v_cndmask_b32_e64 v80, v80, v98, s[46:47]
	ds_bpermute_b32 v87, v175, v79
	s_waitcnt lgkmcnt(2)
	v_cndmask_b32_e32 v81, v81, v99, vcc
	v_fmac_f32_e32 v88, v136, v80
	ds_bpermute_b32 v85, v175, v77
	v_fmac_f32_e32 v88, v132, v81
	v_mul_f32_e32 v80, 0xbfb8aa3b, v88
	v_exp_f32_e32 v80, v80
	s_waitcnt lgkmcnt(2)
	v_cndmask_b32_e64 v81, v82, v100, s[46:47]
	s_waitcnt lgkmcnt(1)
	v_cndmask_b32_e32 v82, v87, v105, vcc
	v_fma_f32 v87, v141, v77, v129
	s_waitcnt lgkmcnt(0)
	v_cndmask_b32_e32 v85, v85, v103, vcc
	v_fmac_f32_e32 v87, v137, v81
	v_add_f32_e32 v80, 1.0, v80
	v_fmac_f32_e32 v87, v133, v85
	ds_bpermute_b32 v84, v173, v78
	v_rcp_f32_e32 v80, v80
	v_mul_f32_e32 v81, 0xbfb8aa3b, v87
	ds_bpermute_b32 v86, v175, v78
	v_exp_f32_e32 v81, v81
	ds_bpermute_b32 v83, v173, v79
	v_pk_mul_f32 v[72:73], v[72:73], v[210:211] op_sel_hi:[1,0]
	v_mul_f32_e32 v80, v88, v80
	s_waitcnt lgkmcnt(2)
	v_cndmask_b32_e64 v84, v84, v102, s[46:47]
	v_mul_f32_e32 v72, v72, v80
	v_add_f32_e32 v80, 1.0, v81
	v_fma_f32 v81, v142, v78, v130
	s_waitcnt lgkmcnt(1)
	v_cndmask_b32_e32 v85, v86, v104, vcc
	v_fmac_f32_e32 v81, v138, v84
	s_waitcnt lgkmcnt(0)
	v_cndmask_b32_e64 v83, v83, v101, s[46:47]
	v_fmac_f32_e32 v81, v134, v85
	v_fma_f32 v85, v143, v79, v131
	v_fmac_f32_e32 v85, v139, v83
	v_mul_f32_e32 v84, 0xbfb8aa3b, v81
	v_fmac_f32_e32 v85, v135, v82
	v_exp_f32_e32 v84, v84
	v_mul_f32_e32 v82, 0xbfb8aa3b, v85
	v_exp_f32_e32 v82, v82
	v_rcp_f32_e32 v80, v80
	v_add_f32_e32 v83, 1.0, v84
	v_rcp_f32_e32 v83, v83
	v_add_f32_e32 v82, 1.0, v82
	v_rcp_f32_e32 v82, v82
	v_mul_f32_e32 v80, v87, v80
	v_pk_mul_f32 v[74:75], v[74:75], v[210:211] op_sel_hi:[1,0]
	v_mul_f32_e32 v73, v73, v80
	v_mul_f32_e32 v80, v81, v83
	v_pk_mul_f32 v[70:71], v[70:71], v[210:211] op_sel_hi:[1,0]
	v_mul_f32_e32 v74, v74, v80
	v_mul_f32_e32 v80, v85, v82
	ds_bpermute_b32 v85, v173, v71
	ds_bpermute_b32 v86, v175, v71
	v_fma_f32 v88, v127, v71, v115
	v_pk_mul_f32 v[68:69], v[68:69], v[210:211] op_sel_hi:[1,0]
	ds_bpermute_b32 v82, v173, v69
	s_waitcnt lgkmcnt(2)
	v_cndmask_b32_e64 v85, v85, v107, s[46:47]
	s_waitcnt lgkmcnt(1)
	v_cndmask_b32_e32 v86, v86, v144, vcc
	v_fmac_f32_e32 v88, v123, v85
	v_fmac_f32_e32 v88, v119, v86
	v_mul_f32_e32 v85, 0xbfb8aa3b, v88
	v_exp_f32_e32 v85, v85
	ds_bpermute_b32 v84, v173, v70
	ds_bpermute_b32 v87, v175, v70
	ds_bpermute_b32 v83, v175, v69
	v_add_f32_e32 v85, 1.0, v85
	v_rcp_f32_e32 v85, v85
	v_mul_f32_e32 v75, v75, v80
	ds_bpermute_b32 v80, v173, v68
	ds_bpermute_b32 v81, v175, v68
	v_pk_mul_f32 v[66:67], v[66:67], v[210:211] op_sel_hi:[1,0]
	v_mul_f32_e32 v85, v88, v85
	s_waitcnt lgkmcnt(5)
	v_cndmask_b32_e64 v82, v82, v94, s[46:47]
	s_waitcnt lgkmcnt(4)
	v_cndmask_b32_e64 v84, v84, v106, s[46:47]
	s_waitcnt lgkmcnt(3)
	v_cndmask_b32_e32 v86, v87, v145, vcc
	v_fma_f32 v87, v126, v70, v114
	v_mul_f32_e32 v67, v67, v85
	v_fma_f32 v85, v125, v69, v113
	v_fmac_f32_e32 v87, v122, v84
	s_waitcnt lgkmcnt(2)
	v_cndmask_b32_e32 v83, v83, v95, vcc
	v_fmac_f32_e32 v85, v121, v82
	s_waitcnt lgkmcnt(1)
	v_cndmask_b32_e64 v80, v80, v92, s[46:47]
	v_fmac_f32_e32 v87, v118, v86
	v_fmac_f32_e32 v85, v117, v83
	v_fma_f32 v83, v124, v68, v112
	s_waitcnt lgkmcnt(0)
	v_cndmask_b32_e32 v81, v81, v93, vcc
	v_mul_f32_e32 v84, 0xbfb8aa3b, v87
	v_fmac_f32_e32 v83, v120, v80
	v_exp_f32_e32 v84, v84
	v_mul_f32_e32 v82, 0xbfb8aa3b, v85
	v_fmac_f32_e32 v83, v116, v81
	v_exp_f32_e32 v82, v82
	v_mul_f32_e32 v80, 0xbfb8aa3b, v83
	v_exp_f32_e32 v80, v80
	v_add_f32_e32 v84, 1.0, v84
	v_rcp_f32_e32 v84, v84
	v_add_f32_e32 v82, 1.0, v82
	v_rcp_f32_e32 v82, v82
	v_add_f32_e32 v80, 1.0, v80
	v_rcp_f32_e32 v80, v80
	v_mul_f32_e32 v81, v87, v84
	v_pk_mul_f32 v[64:65], v[64:65], v[210:211] op_sel_hi:[1,0]
	v_mul_f32_e32 v81, v66, v81
	v_mul_f32_e32 v66, v85, v82
	v_mul_f32_e32 v66, v65, v66
	v_mul_f32_e32 v65, v83, v80
	v_mul_f32_e32 v80, v64, v65
	v_cvt_pk_bf16_f32 v64, v72, v73
	v_mad_i64_i32 v[72:73], s[6:7], v196, s25, v[96:97]
	v_cmp_lt_u32_e64 s[44:45], 13, v176
	v_lshl_add_u64 v[148:149], v[176:177], 0, -12
	v_lshl_add_u64 v[72:73], v[72:73], 0, v[150:151]
	v_cvt_pk_bf16_f32 v65, v74, v75
	v_cvt_pk_bf16_f32 v66, v80, v66
	v_cvt_pk_bf16_f32 v67, v81, v67
	global_store_dwordx4 v[72:73], v[64:67], off sc1
	s_and_saveexec_b64 s[6:7], s[44:45]
	s_cbranch_execz .LBB0_779
	v_lshl_add_u64 v[72:73], v[148:149], 0, s[0:1]
	v_cvt_pk_bf16_f32 v64, v76, v77
	v_cvt_pk_bf16_f32 v65, v78, v79
	v_cvt_pk_bf16_f32 v66, v68, v69
	v_mov_b64_e32 v[68:69], s[54:55]
	v_mad_u64_u32 v[68:69], s[0:1], v72, s25, v[68:69]
	v_mad_i32_i24 v69, v73, s25, v69
	v_lshl_add_u64 v[68:69], v[192:193], 1, v[68:69]
	v_cvt_pk_bf16_f32 v67, v70, v71
	global_store_dwordx4 v[68:69], v[64:67], off sc1
